# window branch: chunks wholly 128..511 behind the wave's tokens take a constant-bias unmasked score path (identical arithmetic), others keep the pipelined bias lookups
# speedup vs baseline: 1.0092x; 1.0005x over previous
.LBB0_685:
	s_or_b64 exec, exec, s[0:1]
	v_lshl_add_u64 v[146:147], v[158:159], 0, v[162:163]
	global_load_dwordx2 v[68:69], v[146:147], off
	global_load_dwordx2 v[104:105], v[146:147], off offset:32
	global_load_dwordx2 v[106:107], v[146:147], off offset:64
	global_load_dwordx2 v[108:109], v[146:147], off offset:96
	global_load_dwordx2 v[110:111], v[146:147], off offset:128
	global_load_dwordx2 v[112:113], v[146:147], off offset:160
	global_load_dwordx2 v[114:115], v[146:147], off offset:192
	global_load_dwordx2 v[240:241], v[146:147], off offset:224
	v_pk_mul_f32 v[64:65], v[64:65], v[30:31] op_sel_hi:[1,0]
	v_pk_mul_f32 v[66:67], v[66:67], v[30:31] op_sel_hi:[1,0]
	s_waitcnt vmcnt(7)
	v_lshlrev_b32_e32 v29, 16, v68
	v_add_f32_e32 v29, v64, v29
	v_and_b32_e32 v31, 0xffff0000, v68
	v_lshlrev_b32_e32 v64, 16, v69
	v_add_f32_e32 v31, v65, v31
	v_add_f32_e32 v65, v66, v64
	v_and_b32_e32 v64, 0xffff0000, v69
	v_add_f32_e32 v66, v67, v64
	v_cvt_pk_bf16_f32 v64, v29, v31
	v_cvt_pk_bf16_f32 v65, v65, v66
	global_store_dwordx2 v[146:147], v[64:65], off
	v_pk_mul_f32 v[60:61], v[60:61], v[30:31] op_sel_hi:[1,0]
	v_pk_mul_f32 v[62:63], v[62:63], v[30:31] op_sel_hi:[1,0]
	s_waitcnt vmcnt(7)
	v_lshlrev_b32_e32 v29, 16, v104
	v_add_f32_e32 v29, v60, v29
	v_and_b32_e32 v31, 0xffff0000, v104
	v_lshlrev_b32_e32 v60, 16, v105
	v_add_f32_e32 v31, v61, v31
	v_add_f32_e32 v61, v62, v60
	v_and_b32_e32 v60, 0xffff0000, v105
	v_add_f32_e32 v62, v63, v60
	v_cvt_pk_bf16_f32 v60, v29, v31
	v_cvt_pk_bf16_f32 v61, v61, v62
	global_store_dwordx2 v[146:147], v[60:61], off offset:32
	v_pk_mul_f32 v[56:57], v[56:57], v[30:31] op_sel_hi:[1,0]
	v_pk_mul_f32 v[58:59], v[58:59], v[30:31] op_sel_hi:[1,0]
	s_waitcnt vmcnt(7)
	v_lshlrev_b32_e32 v29, 16, v106
	v_add_f32_e32 v29, v56, v29
	v_and_b32_e32 v31, 0xffff0000, v106
	v_lshlrev_b32_e32 v56, 16, v107
	v_add_f32_e32 v31, v57, v31
	v_add_f32_e32 v57, v58, v56
	v_and_b32_e32 v56, 0xffff0000, v107
	v_add_f32_e32 v58, v59, v56
	v_cvt_pk_bf16_f32 v56, v29, v31
	v_cvt_pk_bf16_f32 v57, v57, v58
	global_store_dwordx2 v[146:147], v[56:57], off offset:64
	v_pk_mul_f32 v[52:53], v[52:53], v[30:31] op_sel_hi:[1,0]
	v_pk_mul_f32 v[54:55], v[54:55], v[30:31] op_sel_hi:[1,0]
	s_waitcnt vmcnt(7)
	v_lshlrev_b32_e32 v29, 16, v108
	v_add_f32_e32 v29, v52, v29
	v_and_b32_e32 v31, 0xffff0000, v108
	v_lshlrev_b32_e32 v52, 16, v109
	v_add_f32_e32 v31, v53, v31
	v_add_f32_e32 v53, v54, v52
	v_and_b32_e32 v52, 0xffff0000, v109
	v_add_f32_e32 v54, v55, v52
	v_cvt_pk_bf16_f32 v52, v29, v31
	v_cvt_pk_bf16_f32 v53, v53, v54
	global_store_dwordx2 v[146:147], v[52:53], off offset:96
	v_pk_mul_f32 v[48:49], v[48:49], v[30:31] op_sel_hi:[1,0]
	v_pk_mul_f32 v[50:51], v[50:51], v[30:31] op_sel_hi:[1,0]
	s_waitcnt vmcnt(7)
	v_lshlrev_b32_e32 v29, 16, v110
	v_add_f32_e32 v29, v48, v29
	v_and_b32_e32 v31, 0xffff0000, v110
	v_lshlrev_b32_e32 v48, 16, v111
	v_add_f32_e32 v31, v49, v31
	v_add_f32_e32 v49, v50, v48
	v_and_b32_e32 v48, 0xffff0000, v111
	v_add_f32_e32 v50, v51, v48
	v_cvt_pk_bf16_f32 v48, v29, v31
	v_cvt_pk_bf16_f32 v49, v49, v50
	global_store_dwordx2 v[146:147], v[48:49], off offset:128
	v_pk_mul_f32 v[44:45], v[44:45], v[30:31] op_sel_hi:[1,0]
	v_pk_mul_f32 v[46:47], v[46:47], v[30:31] op_sel_hi:[1,0]
	s_waitcnt vmcnt(7)
	v_lshlrev_b32_e32 v29, 16, v112
	v_add_f32_e32 v29, v44, v29
	v_and_b32_e32 v31, 0xffff0000, v112
	v_lshlrev_b32_e32 v44, 16, v113
	v_add_f32_e32 v31, v45, v31
	v_add_f32_e32 v45, v46, v44
	v_and_b32_e32 v44, 0xffff0000, v113
	v_add_f32_e32 v46, v47, v44
	v_cvt_pk_bf16_f32 v44, v29, v31
	v_cvt_pk_bf16_f32 v45, v45, v46
	global_store_dwordx2 v[146:147], v[44:45], off offset:160
	v_pk_mul_f32 v[40:41], v[40:41], v[30:31] op_sel_hi:[1,0]
	v_pk_mul_f32 v[42:43], v[42:43], v[30:31] op_sel_hi:[1,0]
	s_waitcnt vmcnt(7)
	v_lshlrev_b32_e32 v29, 16, v114
	v_add_f32_e32 v29, v40, v29
	v_and_b32_e32 v31, 0xffff0000, v114
	v_lshlrev_b32_e32 v40, 16, v115
	v_add_f32_e32 v31, v41, v31
	v_add_f32_e32 v41, v42, v40
	v_and_b32_e32 v40, 0xffff0000, v115
	v_add_f32_e32 v42, v43, v40
	v_cvt_pk_bf16_f32 v40, v29, v31
	v_cvt_pk_bf16_f32 v41, v41, v42
	global_store_dwordx2 v[146:147], v[40:41], off offset:192
	v_pk_mul_f32 v[38:39], v[38:39], v[30:31] op_sel_hi:[1,0]
	v_pk_mul_f32 v[30:31], v[36:37], v[30:31] op_sel_hi:[1,0]
	s_waitcnt vmcnt(7)
	v_lshlrev_b32_e32 v29, 16, v240
	v_add_f32_e32 v29, v30, v29
	v_and_b32_e32 v30, 0xffff0000, v240
	v_add_f32_e32 v30, v31, v30
	v_lshlrev_b32_e32 v31, 16, v241
	v_add_f32_e32 v31, v38, v31
	v_and_b32_e32 v36, 0xffff0000, v241
	v_add_f32_e32 v36, v39, v36
	v_cvt_pk_bf16_f32 v30, v29, v30
	v_cvt_pk_bf16_f32 v31, v31, v36
	global_store_dwordx2 v[146:147], v[30:31], off offset:224
	s_addk_i32 s68, 0xfe01
	s_lshr_b32 s0, s68, 6
	s_cmp_gt_i32 s67, 7
	s_cselect_b32 s2, s0, 0
	s_sub_i32 s16, s67, s2
	v_cmp_ge_i32_e32 vcc, s16, v154
	s_and_saveexec_b64 s[0:1], vcc
	v_add_u32_e32 v29, s2, v154
	ds_write_b32 v188, v29
	s_or_b64 exec, exec, s[0:1]
	s_cmp_eq_u32 s16, -1
	s_waitcnt lgkmcnt(0)
	s_barrier
	s_cbranch_scc1 .LBB0_711
	v_mov_b32_e32 v29, s50
	ds_read_b32 v29, v29
	s_lshl_b32 s0, s26, 1
	s_add_u32 s0, s64, s0
	s_addc_u32 s1, s65, 0
	s_lshl_b32 s2, s27, 1
	s_waitcnt lgkmcnt(0)
	v_lshlrev_b32_e32 v36, 6, v29
	s_add_u32 s10, s47, s2
	s_mov_b32 s2, 0x60000
	v_ashrrev_i32_e32 v37, 31, v36
	v_add_u32_e32 v53, 0x200, v154
	s_addc_u32 s11, s46, 0
	v_mul_hi_i32 v31, v29, s2
	v_mul_lo_u32 v30, v29, s2
	v_lshlrev_b64 v[36:37], 1, v[36:37]
	v_lshlrev_b32_e32 v29, 3, v154
	v_lshrrev_b32_e32 v52, 4, v154
	s_movk_i32 s2, 0xc00
	v_lshrrev_b32_e32 v54, 4, v53
	v_lshl_add_u64 v[48:49], s[10:11], 0, v[36:37]
	v_and_b32_e32 v40, 0x78, v29
	v_mul_lo_u32 v36, v52, s2
	v_mul_lo_u32 v41, v54, s2
	v_lshl_add_u64 v[30:31], s[0:1], 0, v[30:31]
	v_or_b32_e32 v158, v36, v40
	v_mov_b32_e32 v159, v28
	v_or_b32_e32 v162, v41, v40
	v_mov_b32_e32 v163, v28
	v_lshl_add_u64 v[36:37], v[158:159], 1, v[30:31]
	v_lshl_add_u64 v[30:31], v[162:163], 1, v[30:31]
	global_load_dwordx4 v[36:39], v[36:37], off
	v_and_b32_e32 v29, 56, v29
	global_load_dwordx4 v[40:43], v[30:31], off
	v_lshlrev_b32_e32 v30, 10, v154
	s_movk_i32 s2, 0xe000
	v_and_or_b32 v164, v30, s2, v29
	v_mov_b32_e32 v165, v28
	v_lshl_add_u64 v[30:31], v[164:165], 1, v[48:49]
	global_load_dwordx4 v[44:47], v[30:31], off
	v_lshlrev_b32_e32 v30, 10, v53
	v_and_or_b32 v166, v30, s2, v29
	v_mov_b32_e32 v167, v28
	v_lshl_add_u64 v[30:31], v[166:167], 1, v[48:49]
	global_load_dwordx4 v[48:51], v[30:31], off
	v_lshlrev_b32_e32 v30, 4, v154
	v_and_b32_e32 v29, 0xf0, v30
	v_add_u32_e32 v31, s54, v29
	v_mul_lo_u32 v157, v52, s83
	v_add_u32_e32 v161, v31, v157
	v_mul_lo_u32 v168, v54, s83
	v_and_b32_e32 v30, 0x70, v30
	v_add_u32_e32 v169, v31, v168
	v_add_u32_e32 v31, s79, v30
	s_cmp_lt_i32 s16, 0
	s_waitcnt vmcnt(0)
	ds_write_b128 v161, v[36:39]
	v_lshrrev_b32_e32 v36, 3, v154
	v_mul_lo_u32 v154, v36, s88
	v_lshrrev_b32_e32 v36, 3, v53
	v_mul_lo_u32 v171, v36, s88
	v_add_u32_e32 v170, v31, v154
	v_add_u32_e32 v172, v31, v171
	ds_write_b128 v169, v[40:43]
	ds_write_b128 v170, v[44:47]
	ds_write_b128 v172, v[48:51]
	s_waitcnt lgkmcnt(0)
	s_barrier
	s_cbranch_scc1 .LBB0_712
	v_ashrrev_i32_e32 v39, 4, v155
	v_and_b32_e32 v31, 15, v155
	v_and_b32_e32 v36, -16, v155
	v_lshlrev_b32_e32 v155, 2, v39
	v_lshlrev_b32_e32 v39, 3, v39
	v_add_u32_e32 v37, s54, v36
	v_mul_u32_u24_e32 v38, 0x110, v31
	v_add_u32_e32 v40, s79, v39
	v_mul_u32_u24_e32 v41, 0x90, v31
	v_add_u32_e32 v173, 0, v30
	v_add_u32_e32 v36, 0, v36
	v_add_u32_e32 v39, 0, v39
	v_mov_b32_e32 v30, v28
	v_mov_b32_e32 v31, v28
	v_add_u32_e32 v174, 0, v29
	v_mov_b32_e32 v29, v28
	v_add_u32_e32 v176, v37, v38
	v_add_u32_e32 v177, v40, v41
	v_add_u32_e32 v178, v36, v38
	v_add_u32_e32 v179, v39, v41
	v_mov_b64_e32 v[38:39], v[30:31]
	v_mov_b64_e32 v[42:43], v[30:31]
	v_mov_b64_e32 v[46:47], v[30:31]
	v_mov_b64_e32 v[50:51], v[30:31]
	v_mov_b64_e32 v[54:55], v[30:31]
	v_mov_b64_e32 v[58:59], v[30:31]
	v_mov_b64_e32 v[62:63], v[30:31]
	v_mov_b64_e32 v[66:67], v[30:31]
	v_mov_b64_e32 v[70:71], v[30:31]
	v_mov_b64_e32 v[74:75], v[30:31]
	v_mov_b64_e32 v[78:79], v[30:31]
	v_mov_b64_e32 v[82:83], v[30:31]
	v_mov_b64_e32 v[86:87], v[30:31]
	v_mov_b64_e32 v[90:91], v[30:31]
	v_mov_b64_e32 v[94:95], v[30:31]
	v_mov_b64_e32 v[98:99], v[30:31]
	v_add_u32_e32 v175, -16, v160
	s_add_i32 s17, 0, 0x14848
	s_mov_b32 s18, 0
	v_mov_b32_e32 v180, 0
	v_mov_b32_e32 v182, 0xf149f2ca
	v_mov_b64_e32 v[36:37], v[28:29]
	v_mov_b64_e32 v[40:41], v[28:29]
	v_mov_b64_e32 v[44:45], v[28:29]
	v_mov_b64_e32 v[48:49], v[28:29]
	v_mov_b64_e32 v[52:53], v[28:29]
	v_mov_b64_e32 v[56:57], v[28:29]
	v_mov_b64_e32 v[60:61], v[28:29]
	v_mov_b64_e32 v[64:65], v[28:29]
	v_mov_b64_e32 v[68:69], v[28:29]
	v_mov_b64_e32 v[72:73], v[28:29]
	v_mov_b64_e32 v[76:77], v[28:29]
	v_mov_b64_e32 v[80:81], v[28:29]
	v_mov_b64_e32 v[84:85], v[28:29]
	v_mov_b64_e32 v[88:89], v[28:29]
	v_mov_b64_e32 v[92:93], v[28:29]
	v_mov_b64_e32 v[96:97], v[28:29]
	v_mov_b32_e32 v29, 0xf149f2ca
	v_mov_b32_e32 v181, 0
	ds_read_b32 v239, v151 offset:9728
	v_readfirstlane_b32 s99, v160
	s_waitcnt lgkmcnt(0)
	v_readfirstlane_b32 s32, v239
	s_branch .LBB0_691

.LBB0_693:
	s_setprio 1
	ds_read_b128 v[188:191], v176
	ds_read_b128 v[240:243], v176 offset:64
	ds_read_b128 v[248:251], v176 offset:128
	ds_read_b128 v[252:255], v176 offset:192
	s_waitcnt lgkmcnt(3)
	v_mfma_f32_16x16x32_bf16 v[184:187], v[188:191], v[0:3], 0
	v_mfma_f32_16x16x32_bf16 v[128:131], v[188:191], v[16:19], 0
	ds_read_b128 v[188:191], v176 offset:4352
	s_waitcnt lgkmcnt(3)
	v_mfma_f32_16x16x32_bf16 v[184:187], v[240:243], v[4:7], v[184:187]
	v_mfma_f32_16x16x32_bf16 v[128:131], v[240:243], v[20:23], v[128:131]
	ds_read_b128 v[240:243], v176 offset:4416
	s_waitcnt lgkmcnt(3)
	v_mfma_f32_16x16x32_bf16 v[184:187], v[248:251], v[8:11], v[184:187]
	v_mfma_f32_16x16x32_bf16 v[128:131], v[248:251], v[24:27], v[128:131]
	ds_read_b128 v[248:251], v176 offset:4480
	s_waitcnt lgkmcnt(3)
	v_mfma_f32_16x16x32_bf16 v[184:187], v[252:255], v[12:15], v[184:187]
	v_mfma_f32_16x16x32_bf16 v[128:131], v[252:255], v[32:35], v[128:131]
	ds_read_b128 v[252:255], v176 offset:4544
	s_waitcnt lgkmcnt(3)
	v_mfma_f32_16x16x32_bf16 v[140:143], v[188:191], v[0:3], 0
	v_mfma_f32_16x16x32_bf16 v[124:127], v[188:191], v[16:19], 0
	ds_read_b128 v[188:191], v176 offset:8704
	s_waitcnt lgkmcnt(3)
	v_mfma_f32_16x16x32_bf16 v[140:143], v[240:243], v[4:7], v[140:143]
	v_mfma_f32_16x16x32_bf16 v[124:127], v[240:243], v[20:23], v[124:127]
	ds_read_b128 v[240:243], v176 offset:8768
	s_waitcnt lgkmcnt(3)
	v_mfma_f32_16x16x32_bf16 v[140:143], v[248:251], v[8:11], v[140:143]
	v_mfma_f32_16x16x32_bf16 v[124:127], v[248:251], v[24:27], v[124:127]
	ds_read_b128 v[248:251], v176 offset:8832
	s_waitcnt lgkmcnt(3)
	v_mfma_f32_16x16x32_bf16 v[140:143], v[252:255], v[12:15], v[140:143]
	v_mfma_f32_16x16x32_bf16 v[124:127], v[252:255], v[32:35], v[124:127]
	ds_read_b128 v[252:255], v176 offset:8896
	s_waitcnt lgkmcnt(3)
	v_mfma_f32_16x16x32_bf16 v[136:139], v[188:191], v[0:3], 0
	v_mfma_f32_16x16x32_bf16 v[120:123], v[188:191], v[16:19], 0
	ds_read_b128 v[188:191], v176 offset:13056
	s_waitcnt lgkmcnt(3)
	v_mfma_f32_16x16x32_bf16 v[136:139], v[240:243], v[4:7], v[136:139]
	v_mfma_f32_16x16x32_bf16 v[120:123], v[240:243], v[20:23], v[120:123]
	ds_read_b128 v[240:243], v176 offset:13120
	s_waitcnt lgkmcnt(3)
	v_mfma_f32_16x16x32_bf16 v[136:139], v[248:251], v[8:11], v[136:139]
	v_mfma_f32_16x16x32_bf16 v[120:123], v[248:251], v[24:27], v[120:123]
	ds_read_b128 v[248:251], v176 offset:13184
	s_waitcnt lgkmcnt(3)
	v_mfma_f32_16x16x32_bf16 v[136:139], v[252:255], v[12:15], v[136:139]
	v_mfma_f32_16x16x32_bf16 v[120:123], v[252:255], v[32:35], v[120:123]
	ds_read_b128 v[252:255], v176 offset:13248
	s_waitcnt lgkmcnt(3)
	v_mfma_f32_16x16x32_bf16 v[132:135], v[188:191], v[0:3], 0
	v_mfma_f32_16x16x32_bf16 v[116:119], v[188:191], v[16:19], 0
	s_waitcnt lgkmcnt(2)
	v_mfma_f32_16x16x32_bf16 v[132:135], v[240:243], v[4:7], v[132:135]
	v_mfma_f32_16x16x32_bf16 v[116:119], v[240:243], v[20:23], v[116:119]
	s_waitcnt lgkmcnt(1)
	v_mfma_f32_16x16x32_bf16 v[132:135], v[248:251], v[8:11], v[132:135]
	v_mfma_f32_16x16x32_bf16 v[116:119], v[248:251], v[24:27], v[116:119]
	s_waitcnt lgkmcnt(0)
	v_mfma_f32_16x16x32_bf16 v[132:135], v[252:255], v[12:15], v[132:135]
	v_mfma_f32_16x16x32_bf16 v[116:119], v[252:255], v[32:35], v[116:119]
	s_setprio 0
	v_lshl_add_u32 v189, s2, 6, v155
	s_lshl_b32 s98, s2, 6
	s_sub_i32 s98, s99, s98
	s_add_i32 s98, s98, 0xffffff41
	s_cmp_lt_u32 s98, 0x122
	s_cbranch_scc0 .Lb3s_0
	v_add_f32_e32 v30, s32, v184
	v_add_f32_e32 v184, s32, v185
	v_add_f32_e32 v185, s32, v186
	v_add_f32_e32 v186, s32, v187
	v_add_f32_e32 v140, s32, v140
	v_add_f32_e32 v141, s32, v141
	v_add_f32_e32 v142, s32, v142
	v_add_f32_e32 v143, s32, v143
	v_add_f32_e32 v136, s32, v136
	v_add_f32_e32 v187, s32, v137
	v_add_f32_e32 v188, s32, v138
	v_add_f32_e32 v217, s32, v139
	v_add_f32_e32 v218, s32, v132
	v_add_f32_e32 v219, s32, v133
	v_add_f32_e32 v220, s32, v134
	v_add_f32_e32 v135, s32, v135
	v_max3_f32 v132, v30, s82, v184
	v_max3_f32 v132, v132, v185, v186
	v_max3_f32 v132, v132, v140, v141
	v_max3_f32 v132, v132, v142, v143
	v_max3_f32 v132, v132, v136, v187
	v_max3_f32 v132, v132, v188, v217
	v_max3_f32 v132, v132, v218, v219
	v_max3_f32 v132, v132, v220, v135
	s_branch .Lb3e_0
.Lb3s_0:
	v_sub_u32_e32 v239, v160, v189
	v_med3_i32 v239, v239, 0, v207
	v_lshl_add_u32 v239, v239, 2, v151
	ds_read_b32 v31, v239 offset:9216
	v_or_b32_e32 v240, 1, v189
	v_sub_u32_e32 v240, v160, v240
	v_med3_i32 v240, v240, 0, v207
	v_lshl_add_u32 v240, v240, 2, v151
	ds_read_b32 v240, v240 offset:9216
	v_or_b32_e32 v241, 2, v189
	v_sub_u32_e32 v241, v160, v241
	v_med3_i32 v241, v241, 0, v207
	v_lshl_add_u32 v241, v241, 2, v151
	ds_read_b32 v241, v241 offset:9216
	v_or_b32_e32 v242, 3, v189
	v_sub_u32_e32 v242, v160, v242
	v_med3_i32 v242, v242, 0, v207
	v_lshl_add_u32 v242, v242, 2, v151
	ds_read_b32 v242, v242 offset:9216
	v_sub_u32_e32 v243, v175, v189
	v_med3_i32 v243, v243, 0, v207
	v_lshl_add_u32 v243, v243, 2, v151
	ds_read_b32 v243, v243 offset:9216
	v_add_u32_e32 v247, 17, v189
	v_sub_u32_e32 v247, v160, v247
	v_med3_i32 v247, v247, 0, v207
	v_lshl_add_u32 v247, v247, 2, v151
	ds_read_b32 v247, v247 offset:9216
	v_add_u32_e32 v248, 18, v189
	v_sub_u32_e32 v248, v160, v248
	v_med3_i32 v248, v248, 0, v207
	v_lshl_add_u32 v248, v248, 2, v151
	ds_read_b32 v248, v248 offset:9216
	v_add_u32_e32 v249, 19, v189
	v_sub_u32_e32 v249, v160, v249
	v_med3_i32 v249, v249, 0, v207
	v_lshl_add_u32 v249, v249, 2, v151
	ds_read_b32 v249, v249 offset:9216
	v_add_u32_e32 v250, 32, v189
	v_sub_u32_e32 v250, v160, v250
	v_med3_i32 v250, v250, 0, v207
	v_lshl_add_u32 v250, v250, 2, v151
	ds_read_b32 v250, v250 offset:9216
	v_add_u32_e32 v251, 33, v189
	v_sub_u32_e32 v251, v160, v251
	v_med3_i32 v251, v251, 0, v207
	v_lshl_add_u32 v251, v251, 2, v151
	ds_read_b32 v251, v251 offset:9216
	v_add_u32_e32 v252, 34, v189
	v_sub_u32_e32 v252, v160, v252
	v_med3_i32 v252, v252, 0, v207
	v_lshl_add_u32 v252, v252, 2, v151
	ds_read_b32 v252, v252 offset:9216
	v_add_u32_e32 v253, 35, v189
	v_sub_u32_e32 v253, v160, v253
	v_med3_i32 v253, v253, 0, v207
	v_lshl_add_u32 v253, v253, 2, v151
	ds_read_b32 v253, v253 offset:9216
	v_add_u32_e32 v254, 48, v189
	v_sub_u32_e32 v254, v160, v254
	v_med3_i32 v254, v254, 0, v207
	v_lshl_add_u32 v254, v254, 2, v151
	ds_read_b32 v254, v254 offset:9216
	v_add_u32_e32 v255, 49, v189
	v_sub_u32_e32 v255, v160, v255
	v_med3_i32 v255, v255, 0, v207
	v_lshl_add_u32 v255, v255, 2, v151
	ds_read_b32 v255, v255 offset:9216
	v_or_b32_e32 v190, 1, v189
	v_sub_u32_e32 v30, v160, v189
	v_sub_u32_e32 v183, v160, v190
	v_cmp_gt_u32_e64 s[8:9], s75, v30
	v_cmp_gt_u32_e32 vcc, s75, v183
	v_or_b32_e32 v191, 2, v189
	v_or_b32_e32 v192, 3, v189
	v_add_u32_e32 v213, 17, v189
	s_waitcnt lgkmcnt(13)
	v_add_f32_e32 v30, v184, v31
	s_waitcnt lgkmcnt(12)
	v_add_f32_e32 v183, v185, v240
	v_sub_u32_e32 v185, v160, v191
	v_cndmask_b32_e32 v184, v208, v183, vcc
	v_cmp_gt_u32_e32 vcc, s75, v185
	v_add_u32_e32 v214, 18, v189
	v_add_u32_e32 v215, 19, v189
	v_add_u32_e32 v216, 32, v189
	v_add_u32_e32 v193, 33, v189
	s_waitcnt lgkmcnt(11)
	v_add_f32_e32 v185, v186, v241
	v_sub_u32_e32 v186, v160, v192
	v_cndmask_b32_e32 v185, v208, v185, vcc
	v_cmp_gt_u32_e32 vcc, s75, v186
	v_cndmask_b32_e64 v30, v208, v30, s[8:9]
	v_max3_f32 v183, v30, s82, v184
	v_add_u32_e32 v194, 34, v189
	v_add_u32_e32 v195, 35, v189
	s_waitcnt lgkmcnt(10)
	v_add_f32_e32 v186, v187, v242
	v_sub_u32_e32 v187, v175, v189
	v_cndmask_b32_e32 v186, v208, v186, vcc
	v_cmp_gt_u32_e32 vcc, s75, v187
	v_max3_f32 v183, v183, v185, v186
	v_add_u32_e32 v209, 48, v189
	v_add_u32_e32 v210, 49, v189
	v_add_u32_e32 v211, 50, v189
	s_waitcnt lgkmcnt(9)
	v_add_f32_e32 v140, v140, v243
	v_sub_u32_e32 v187, v160, v213
	v_cndmask_b32_e32 v140, v208, v140, vcc
	v_cmp_gt_u32_e32 vcc, s75, v187
	v_add_u32_e32 v212, 51, v189
	s_waitcnt lgkmcnt(8)
	v_add_f32_e32 v141, v141, v247
	v_sub_u32_e32 v187, v160, v214
	v_cndmask_b32_e32 v141, v208, v141, vcc
	v_cmp_gt_u32_e32 vcc, s75, v187
	v_max3_f32 v183, v183, v140, v141
	s_waitcnt lgkmcnt(7)
	v_add_f32_e32 v142, v142, v248
	v_sub_u32_e32 v187, v160, v215
	v_cndmask_b32_e32 v142, v208, v142, vcc
	v_cmp_gt_u32_e32 vcc, s75, v187
	s_waitcnt lgkmcnt(6)
	v_add_f32_e32 v143, v143, v249
	v_sub_u32_e32 v187, v160, v216
	v_cndmask_b32_e32 v143, v208, v143, vcc
	v_cmp_gt_u32_e32 vcc, s75, v187
	v_max3_f32 v183, v183, v142, v143
	s_waitcnt lgkmcnt(5)
	v_add_f32_e32 v136, v136, v250
	v_sub_u32_e32 v187, v160, v193
	v_cndmask_b32_e32 v136, v208, v136, vcc
	v_cmp_gt_u32_e32 vcc, s75, v187
	s_waitcnt lgkmcnt(4)
	v_add_f32_e32 v137, v137, v251
	v_cndmask_b32_e32 v187, v208, v137, vcc
	v_max3_f32 v137, v183, v136, v187
	v_sub_u32_e32 v183, v160, v194
	v_cmp_gt_u32_e32 vcc, s75, v183
	s_waitcnt lgkmcnt(3)
	v_add_f32_e32 v138, v138, v252
	v_cndmask_b32_e32 v188, v208, v138, vcc
	v_sub_u32_e32 v138, v160, v195
	v_cmp_gt_u32_e32 vcc, s75, v138
	s_waitcnt lgkmcnt(2)
	v_add_f32_e32 v138, v139, v253
	v_cndmask_b32_e32 v217, v208, v138, vcc
	v_sub_u32_e32 v138, v160, v209
	v_cmp_gt_u32_e32 vcc, s75, v138
	v_max3_f32 v137, v137, v188, v217
	s_waitcnt lgkmcnt(1)
	v_add_f32_e32 v132, v132, v254
	v_cndmask_b32_e32 v218, v208, v132, vcc
	v_sub_u32_e32 v132, v160, v210
	v_cmp_gt_u32_e32 vcc, s75, v132
	s_waitcnt lgkmcnt(0)
	v_add_f32_e32 v132, v133, v255
	v_sub_u32_e32 v133, v160, v211
	v_cndmask_b32_e32 v219, v208, v132, vcc
	v_cmp_gt_u32_e32 vcc, s75, v133
	v_med3_i32 v133, v133, 0, v207
	v_lshl_add_u32 v133, v133, 2, v151
	ds_read_b32 v133, v133 offset:9216
	v_max3_f32 v132, v137, v218, v219
	s_waitcnt lgkmcnt(0)
	v_add_f32_e32 v133, v134, v133
	v_cndmask_b32_e32 v220, v208, v133, vcc
	v_sub_u32_e32 v133, v160, v212
	v_cmp_gt_u32_e32 vcc, s75, v133
	v_med3_i32 v133, v133, 0, v207
	v_lshl_add_u32 v133, v133, 2, v151
	ds_read_b32 v133, v133 offset:9216
	s_waitcnt lgkmcnt(0)
	v_add_f32_e32 v133, v135, v133
	v_cndmask_b32_e32 v135, v208, v133, vcc
	v_max3_f32 v132, v132, v220, v135
.Lb3e_0:
	v_mov_b32_e32 v133, v132
	s_nop 1
	v_permlane16_swap_b32_e32 v132, v133
	v_max_f32_e32 v133, v133, v133
	v_max_f32_e32 v132, v132, v132
	v_max_f32_e32 v132, v132, v133
	v_mov_b32_e32 v133, v132
	s_nop 1
	v_permlane32_swap_b32_e32 v132, v133
	v_max3_f32 v183, v29, v132, v133
	v_sub_f32_e32 v29, v29, v183
	v_mul_f32_e32 v221, 0x3fb8aa3b, v29
	v_sub_f32_e32 v29, v30, v183
	v_mul_f32_e32 v29, 0x3fb8aa3b, v29
	v_sub_f32_e32 v132, v184, v183
	v_exp_f32_e32 v29, v29
	v_mul_f32_e32 v132, 0x3fb8aa3b, v132
	v_sub_f32_e32 v133, v185, v183
	v_exp_f32_e32 v132, v132
	v_mul_f32_e32 v133, 0x3fb8aa3b, v133
	v_sub_f32_e32 v134, v186, v183
	v_exp_f32_e32 v133, v133
	v_mul_f32_e32 v134, 0x3fb8aa3b, v134
	v_cmp_lt_f32_e32 vcc, s51, v30
	v_exp_f32_e32 v134, v134
	s_nop 0
	v_cndmask_b32_e32 v29, 0, v29, vcc
	v_cmp_lt_f32_e32 vcc, s51, v184
	v_add_f32_e32 v30, 0, v29
	s_nop 0
	v_cndmask_b32_e32 v132, 0, v132, vcc
	v_cmp_lt_f32_e32 vcc, s51, v185
	v_add_f32_e32 v30, v132, v30
	s_nop 0
	v_cndmask_b32_e32 v133, 0, v133, vcc
	v_cmp_lt_f32_e32 vcc, s51, v186
	v_add_f32_e32 v30, v133, v30
	s_nop 0
	v_cndmask_b32_e32 v137, 0, v134, vcc
	v_sub_f32_e32 v134, v140, v183
	v_mul_f32_e32 v134, 0x3fb8aa3b, v134
	v_exp_f32_e32 v134, v134
	v_cmp_lt_f32_e32 vcc, s51, v140
	v_add_f32_e32 v30, v137, v30
	s_nop 0
	v_cndmask_b32_e32 v138, 0, v134, vcc
	v_sub_f32_e32 v134, v141, v183
	v_mul_f32_e32 v134, 0x3fb8aa3b, v134
	v_exp_f32_e32 v134, v134
	v_cmp_lt_f32_e32 vcc, s51, v141
	v_add_f32_e32 v30, v138, v30
	s_nop 0
	v_cndmask_b32_e32 v141, 0, v134, vcc
	v_sub_f32_e32 v134, v142, v183
	v_mul_f32_e32 v134, 0x3fb8aa3b, v134
	v_exp_f32_e32 v134, v134
	v_cmp_lt_f32_e32 vcc, s51, v142
	v_add_f32_e32 v30, v141, v30
	s_nop 0
	v_cndmask_b32_e32 v142, 0, v134, vcc
	v_sub_f32_e32 v134, v143, v183
	v_mul_f32_e32 v134, 0x3fb8aa3b, v134
	v_exp_f32_e32 v134, v134
	v_cmp_lt_f32_e32 vcc, s51, v143
	v_add_f32_e32 v30, v142, v30
	s_nop 0
	v_cndmask_b32_e32 v185, 0, v134, vcc
	v_sub_f32_e32 v134, v136, v183
	v_cmp_lt_f32_e32 vcc, s51, v136
	v_mul_f32_e32 v134, 0x3fb8aa3b, v134
	v_sub_f32_e32 v136, v187, v183
	v_exp_f32_e32 v134, v134
	v_mul_f32_e32 v136, 0x3fb8aa3b, v136
	v_exp_f32_e32 v136, v136
	v_add_f32_e32 v30, v185, v30
	v_cndmask_b32_e32 v134, 0, v134, vcc
	v_cmp_lt_f32_e32 vcc, s51, v187
	v_add_f32_e32 v30, v134, v30
	s_nop 0
	v_cndmask_b32_e32 v139, 0, v136, vcc
	v_sub_f32_e32 v136, v188, v183
	v_mul_f32_e32 v136, 0x3fb8aa3b, v136
	v_exp_f32_e32 v136, v136
	v_cmp_lt_f32_e32 vcc, s51, v188
	v_add_f32_e32 v30, v139, v30
	s_nop 0
	v_cndmask_b32_e32 v140, 0, v136, vcc
	v_sub_f32_e32 v136, v217, v183
	v_mul_f32_e32 v136, 0x3fb8aa3b, v136
	v_exp_f32_e32 v136, v136
	v_cmp_lt_f32_e32 vcc, s51, v217
	v_add_f32_e32 v30, v140, v30
	s_nop 0
	v_cndmask_b32_e32 v143, 0, v136, vcc
	v_sub_f32_e32 v136, v218, v183
	v_mul_f32_e32 v136, 0x3fb8aa3b, v136
	v_exp_f32_e32 v136, v136
	v_cmp_lt_f32_e32 vcc, s51, v218
	v_add_f32_e32 v30, v143, v30
	s_nop 0
	v_cndmask_b32_e32 v184, 0, v136, vcc
	v_sub_f32_e32 v136, v219, v183
	v_mul_f32_e32 v136, 0x3fb8aa3b, v136
	v_exp_f32_e32 v136, v136
	v_cmp_lt_f32_e32 vcc, s51, v219
	v_add_f32_e32 v30, v184, v30
	s_nop 0
	v_cndmask_b32_e32 v186, 0, v136, vcc
	v_sub_f32_e32 v136, v220, v183
	v_mul_f32_e32 v136, 0x3fb8aa3b, v136
	v_exp_f32_e32 v136, v136
	v_cmp_lt_f32_e32 vcc, s51, v220
	v_add_f32_e32 v30, v186, v30
	s_nop 0
	v_cndmask_b32_e32 v187, 0, v136, vcc
	v_cmp_lt_f32_e32 vcc, s51, v135
	v_sub_f32_e32 v135, v135, v183
	v_mul_f32_e32 v135, 0x3fb8aa3b, v135
	v_exp_f32_e32 v135, v135
	v_add_f32_e32 v30, v187, v30
	v_cndmask_b32_e32 v188, 0, v135, vcc
	v_add_f32_e32 v135, v188, v30
	v_exp_f32_e32 v30, v221
	v_mov_b32_e32 v136, v135
	s_nop 1
	v_permlane16_swap_b32_e32 v135, v136
	v_add_f32_e32 v135, v135, v136
	v_mov_b32_e32 v136, v135
	s_nop 1
	v_permlane32_swap_b32_e32 v135, v136
	v_cmp_neq_f32_e32 vcc, 1.0, v30
	s_cbranch_vccz .LBB0_695
	v_pk_mul_f32 v[98:99], v[98:99], v[30:31] op_sel_hi:[1,0]
	v_pk_mul_f32 v[96:97], v[96:97], v[30:31] op_sel_hi:[1,0]
	v_pk_mul_f32 v[94:95], v[94:95], v[30:31] op_sel_hi:[1,0]
	v_pk_mul_f32 v[92:93], v[92:93], v[30:31] op_sel_hi:[1,0]
	v_pk_mul_f32 v[90:91], v[90:91], v[30:31] op_sel_hi:[1,0]
	v_pk_mul_f32 v[88:89], v[88:89], v[30:31] op_sel_hi:[1,0]
	v_pk_mul_f32 v[86:87], v[86:87], v[30:31] op_sel_hi:[1,0]
	v_pk_mul_f32 v[84:85], v[84:85], v[30:31] op_sel_hi:[1,0]
	v_pk_mul_f32 v[82:83], v[82:83], v[30:31] op_sel_hi:[1,0]
	v_pk_mul_f32 v[80:81], v[80:81], v[30:31] op_sel_hi:[1,0]
	v_pk_mul_f32 v[78:79], v[78:79], v[30:31] op_sel_hi:[1,0]
	v_pk_mul_f32 v[76:77], v[76:77], v[30:31] op_sel_hi:[1,0]
	v_pk_mul_f32 v[74:75], v[74:75], v[30:31] op_sel_hi:[1,0]
	v_pk_mul_f32 v[72:73], v[72:73], v[30:31] op_sel_hi:[1,0]
	v_pk_mul_f32 v[70:71], v[70:71], v[30:31] op_sel_hi:[1,0]
	v_pk_mul_f32 v[68:69], v[68:69], v[30:31] op_sel_hi:[1,0]
.LBB0_695:
	s_lshl_b32 s98, s2, 6
	s_sub_i32 s98, s99, s98
	s_add_i32 s98, s98, 0xffffff41
	s_cmp_lt_u32 s98, 0x122
	s_cbranch_scc0 .Lb3s_1
	v_add_f32_e32 v124, s32, v124
	v_add_f32_e32 v128, s32, v128
	v_add_f32_e32 v129, s32, v129
	v_add_f32_e32 v130, s32, v130
	v_add_f32_e32 v131, s32, v131
	v_add_f32_e32 v125, s32, v125
	v_add_f32_e32 v126, s32, v126
	v_add_f32_e32 v127, s32, v127
	v_add_f32_e32 v120, s32, v120
	v_add_f32_e32 v189, s32, v121
	v_add_f32_e32 v190, s32, v122
	v_add_f32_e32 v123, s32, v123
	v_add_f32_e32 v116, s32, v116
	v_add_f32_e32 v191, s32, v117
	v_add_f32_e32 v192, s32, v118
	v_add_f32_e32 v193, s32, v119
	v_max3_f32 v31, v124, s82, v128
	v_max3_f32 v31, v31, v129, v130
	v_max3_f32 v31, v31, v131, v125
	v_max3_f32 v31, v31, v126, v127
	v_max3_f32 v31, v31, v120, v189
	v_max3_f32 v31, v31, v190, v123
	v_max3_f32 v31, v31, v116, v191
	v_max3_f32 v31, v31, v192, v193
	s_branch .Lb3e_1

.Lb3e_1:
	v_mov_b32_e32 v117, v31
	s_nop 1
	v_permlane16_swap_b32_e32 v31, v117
	v_max_f32_e32 v117, v117, v117
	v_max_f32_e32 v31, v31, v31
	v_max_f32_e32 v31, v31, v117
	v_mov_b32_e32 v117, v31
	s_nop 1
	v_permlane32_swap_b32_e32 v31, v117
	v_max3_f32 v31, v182, v31, v117
	v_sub_f32_e32 v117, v182, v31
	v_mul_f32_e32 v194, 0x3fb8aa3b, v117
	v_sub_f32_e32 v117, v128, v31
	v_mul_f32_e32 v117, 0x3fb8aa3b, v117
	v_sub_f32_e32 v118, v129, v31
	v_exp_f32_e32 v117, v117
	v_mul_f32_e32 v118, 0x3fb8aa3b, v118
	v_exp_f32_e32 v118, v118
	v_cmp_lt_f32_e32 vcc, s51, v128
	s_nop 1
	v_cndmask_b32_e32 v117, 0, v117, vcc
	v_cmp_lt_f32_e32 vcc, s51, v129
	v_add_f32_e32 v119, 0, v117
	s_nop 0
	v_cndmask_b32_e32 v118, 0, v118, vcc
	v_add_f32_e32 v121, v118, v119
	v_sub_f32_e32 v119, v130, v31
	v_mul_f32_e32 v119, 0x3fb8aa3b, v119
	v_exp_f32_e32 v119, v119
	v_cmp_lt_f32_e32 vcc, s51, v130
	s_nop 1
	v_cndmask_b32_e32 v119, 0, v119, vcc
	v_add_f32_e32 v122, v119, v121
	v_sub_f32_e32 v121, v131, v31
	v_mul_f32_e32 v121, 0x3fb8aa3b, v121
	v_exp_f32_e32 v121, v121
	v_cmp_lt_f32_e32 vcc, s51, v131
	s_nop 1
	v_cndmask_b32_e32 v121, 0, v121, vcc
	v_add_f32_e32 v128, v121, v122
	v_sub_f32_e32 v122, v124, v31
	v_mul_f32_e32 v122, 0x3fb8aa3b, v122
	v_exp_f32_e32 v122, v122
	v_cmp_lt_f32_e32 vcc, s51, v124
	s_nop 1
	v_cndmask_b32_e32 v122, 0, v122, vcc
	v_cmp_lt_f32_e32 vcc, s51, v125
	v_sub_f32_e32 v125, v125, v31
	v_mul_f32_e32 v125, 0x3fb8aa3b, v125
	v_exp_f32_e32 v125, v125
	v_add_f32_e32 v124, v122, v128
	v_cndmask_b32_e32 v128, 0, v125, vcc
	v_sub_f32_e32 v125, v126, v31
	v_mul_f32_e32 v125, 0x3fb8aa3b, v125
	v_exp_f32_e32 v125, v125
	v_cmp_lt_f32_e32 vcc, s51, v126
	v_sub_f32_e32 v126, v190, v31
	v_mul_f32_e32 v126, 0x3fb8aa3b, v126
	v_cndmask_b32_e32 v129, 0, v125, vcc
	v_sub_f32_e32 v125, v127, v31
	v_mul_f32_e32 v125, 0x3fb8aa3b, v125
	v_exp_f32_e32 v125, v125
	v_cmp_lt_f32_e32 vcc, s51, v127
	v_exp_f32_e32 v126, v126
	v_add_f32_e32 v124, v128, v124
	v_cndmask_b32_e32 v131, 0, v125, vcc
	v_cmp_lt_f32_e32 vcc, s51, v120
	v_sub_f32_e32 v120, v120, v31
	v_mul_f32_e32 v120, 0x3fb8aa3b, v120
	v_sub_f32_e32 v125, v189, v31
	v_exp_f32_e32 v120, v120
	v_mul_f32_e32 v125, 0x3fb8aa3b, v125
	v_exp_f32_e32 v125, v125
	v_add_f32_e32 v124, v129, v124
	v_cndmask_b32_e32 v120, 0, v120, vcc
	v_cmp_lt_f32_e32 vcc, s51, v189
	v_add_f32_e32 v124, v131, v124
	v_add_f32_e32 v124, v120, v124
	v_cndmask_b32_e32 v125, 0, v125, vcc
	v_cmp_lt_f32_e32 vcc, s51, v190
	v_add_f32_e32 v124, v125, v124
	s_nop 0
	v_cndmask_b32_e32 v126, 0, v126, vcc
	v_cmp_lt_f32_e32 vcc, s51, v123
	v_sub_f32_e32 v123, v123, v31
	v_mul_f32_e32 v123, 0x3fb8aa3b, v123
	v_exp_f32_e32 v123, v123
	v_add_f32_e32 v124, v126, v124
	v_cndmask_b32_e32 v127, 0, v123, vcc
	v_cmp_lt_f32_e32 vcc, s51, v116
	v_sub_f32_e32 v116, v116, v31
	v_mul_f32_e32 v116, 0x3fb8aa3b, v116
	v_exp_f32_e32 v116, v116
	v_add_f32_e32 v123, v127, v124
	v_cndmask_b32_e32 v130, 0, v116, vcc
	v_add_f32_e32 v116, v130, v123
	v_sub_f32_e32 v123, v191, v31
	v_mul_f32_e32 v123, 0x3fb8aa3b, v123
	v_exp_f32_e32 v123, v123
	v_cmp_lt_f32_e32 vcc, s51, v191
	s_nop 1
	v_cndmask_b32_e32 v182, 0, v123, vcc
	v_sub_f32_e32 v123, v192, v31
	v_mul_f32_e32 v123, 0x3fb8aa3b, v123
	v_exp_f32_e32 v123, v123
	v_cmp_lt_f32_e32 vcc, s51, v192
	v_add_f32_e32 v116, v182, v116
	s_nop 0
	v_cndmask_b32_e32 v189, 0, v123, vcc
	v_sub_f32_e32 v123, v193, v31
	v_mul_f32_e32 v123, 0x3fb8aa3b, v123
	v_exp_f32_e32 v123, v123
	v_cmp_lt_f32_e32 vcc, s51, v193
	v_add_f32_e32 v116, v189, v116
	s_nop 0
	v_cndmask_b32_e32 v190, 0, v123, vcc
	v_add_f32_e32 v123, v190, v116
	v_exp_f32_e32 v116, v194
	v_mov_b32_e32 v124, v123
	s_nop 1
	v_permlane16_swap_b32_e32 v123, v124
	v_add_f32_e32 v123, v123, v124
	v_mov_b32_e32 v124, v123
	s_nop 1
	v_permlane32_swap_b32_e32 v123, v124
	v_cmp_neq_f32_e32 vcc, 1.0, v116
	s_cbranch_vccz .LBB0_697
	v_pk_mul_f32 v[66:67], v[66:67], v[116:117] op_sel_hi:[1,0]
	v_pk_mul_f32 v[64:65], v[64:65], v[116:117] op_sel_hi:[1,0]
	v_pk_mul_f32 v[62:63], v[62:63], v[116:117] op_sel_hi:[1,0]
	v_pk_mul_f32 v[60:61], v[60:61], v[116:117] op_sel_hi:[1,0]
	v_pk_mul_f32 v[58:59], v[58:59], v[116:117] op_sel_hi:[1,0]
	v_pk_mul_f32 v[56:57], v[56:57], v[116:117] op_sel_hi:[1,0]
	v_pk_mul_f32 v[54:55], v[54:55], v[116:117] op_sel_hi:[1,0]
	v_pk_mul_f32 v[52:53], v[52:53], v[116:117] op_sel_hi:[1,0]
	v_pk_mul_f32 v[50:51], v[50:51], v[116:117] op_sel_hi:[1,0]
	v_pk_mul_f32 v[48:49], v[48:49], v[116:117] op_sel_hi:[1,0]
	v_pk_mul_f32 v[46:47], v[46:47], v[116:117] op_sel_hi:[1,0]
	v_pk_mul_f32 v[44:45], v[44:45], v[116:117] op_sel_hi:[1,0]
	v_pk_mul_f32 v[42:43], v[42:43], v[116:117] op_sel_hi:[1,0]
	v_pk_mul_f32 v[40:41], v[40:41], v[116:117] op_sel_hi:[1,0]
	v_pk_mul_f32 v[38:39], v[38:39], v[116:117] op_sel_hi:[1,0]
	v_pk_mul_f32 v[36:37], v[36:37], v[116:117] op_sel_hi:[1,0]

.LBB0_704:
	s_setprio 1
	ds_read_b128 v[186:189], v178 offset:11328
	ds_read_b128 v[240:243], v178 offset:11392
	ds_read_b128 v[248:251], v178 offset:11456
	ds_read_b128 v[252:255], v178 offset:11520
	s_waitcnt lgkmcnt(3)
	v_mfma_f32_16x16x32_bf16 v[190:193], v[186:189], v[0:3], 0
	v_mfma_f32_16x16x32_bf16 v[128:131], v[186:189], v[16:19], 0
	ds_read_b128 v[186:189], v178 offset:15680
	s_waitcnt lgkmcnt(3)
	v_mfma_f32_16x16x32_bf16 v[190:193], v[240:243], v[4:7], v[190:193]
	v_mfma_f32_16x16x32_bf16 v[128:131], v[240:243], v[20:23], v[128:131]
	ds_read_b128 v[240:243], v178 offset:15744
	s_waitcnt lgkmcnt(3)
	v_mfma_f32_16x16x32_bf16 v[190:193], v[248:251], v[8:11], v[190:193]
	v_mfma_f32_16x16x32_bf16 v[128:131], v[248:251], v[24:27], v[128:131]
	ds_read_b128 v[248:251], v178 offset:15808
	s_waitcnt lgkmcnt(3)
	v_mfma_f32_16x16x32_bf16 v[190:193], v[252:255], v[12:15], v[190:193]
	v_mfma_f32_16x16x32_bf16 v[128:131], v[252:255], v[32:35], v[128:131]
	ds_read_b128 v[252:255], v178 offset:15872
	s_waitcnt lgkmcnt(3)
	v_mfma_f32_16x16x32_bf16 v[140:143], v[186:189], v[0:3], 0
	v_mfma_f32_16x16x32_bf16 v[124:127], v[186:189], v[16:19], 0
	ds_read_b128 v[186:189], v178 offset:20032
	s_waitcnt lgkmcnt(3)
	v_mfma_f32_16x16x32_bf16 v[140:143], v[240:243], v[4:7], v[140:143]
	v_mfma_f32_16x16x32_bf16 v[124:127], v[240:243], v[20:23], v[124:127]
	ds_read_b128 v[240:243], v178 offset:20096
	s_waitcnt lgkmcnt(3)
	v_mfma_f32_16x16x32_bf16 v[140:143], v[248:251], v[8:11], v[140:143]
	v_mfma_f32_16x16x32_bf16 v[124:127], v[248:251], v[24:27], v[124:127]
	ds_read_b128 v[248:251], v178 offset:20160
	s_waitcnt lgkmcnt(3)
	v_mfma_f32_16x16x32_bf16 v[140:143], v[252:255], v[12:15], v[140:143]
	v_mfma_f32_16x16x32_bf16 v[124:127], v[252:255], v[32:35], v[124:127]
	ds_read_b128 v[252:255], v178 offset:20224
	s_waitcnt lgkmcnt(3)
	v_mfma_f32_16x16x32_bf16 v[136:139], v[186:189], v[0:3], 0
	v_mfma_f32_16x16x32_bf16 v[120:123], v[186:189], v[16:19], 0
	ds_read_b128 v[186:189], v178 offset:24384
	s_waitcnt lgkmcnt(3)
	v_mfma_f32_16x16x32_bf16 v[136:139], v[240:243], v[4:7], v[136:139]
	v_mfma_f32_16x16x32_bf16 v[120:123], v[240:243], v[20:23], v[120:123]
	ds_read_b128 v[240:243], v178 offset:24448
	s_waitcnt lgkmcnt(3)
	v_mfma_f32_16x16x32_bf16 v[136:139], v[248:251], v[8:11], v[136:139]
	v_mfma_f32_16x16x32_bf16 v[120:123], v[248:251], v[24:27], v[120:123]
	ds_read_b128 v[248:251], v178 offset:24512
	s_waitcnt lgkmcnt(3)
	v_mfma_f32_16x16x32_bf16 v[136:139], v[252:255], v[12:15], v[136:139]
	v_mfma_f32_16x16x32_bf16 v[120:123], v[252:255], v[32:35], v[120:123]
	ds_read_b128 v[252:255], v178 offset:24576
	s_waitcnt lgkmcnt(3)
	v_mfma_f32_16x16x32_bf16 v[132:135], v[186:189], v[0:3], 0
	v_mfma_f32_16x16x32_bf16 v[116:119], v[186:189], v[16:19], 0
	s_waitcnt lgkmcnt(2)
	v_mfma_f32_16x16x32_bf16 v[132:135], v[240:243], v[4:7], v[132:135]
	v_mfma_f32_16x16x32_bf16 v[116:119], v[240:243], v[20:23], v[116:119]
	s_waitcnt lgkmcnt(1)
	v_mfma_f32_16x16x32_bf16 v[132:135], v[248:251], v[8:11], v[132:135]
	v_mfma_f32_16x16x32_bf16 v[116:119], v[248:251], v[24:27], v[116:119]
	s_waitcnt lgkmcnt(0)
	v_mfma_f32_16x16x32_bf16 v[132:135], v[252:255], v[12:15], v[132:135]
	v_mfma_f32_16x16x32_bf16 v[116:119], v[252:255], v[32:35], v[116:119]
	s_setprio 0
	v_lshl_add_u32 v189, s2, 6, v155
	s_lshl_b32 s98, s2, 6
	s_sub_i32 s98, s99, s98
	s_add_i32 s98, s98, 0xffffff41
	s_cmp_lt_u32 s98, 0x122
	s_cbranch_scc0 .Lb3s_2
	v_add_f32_e32 v30, s32, v190
	v_add_f32_e32 v180, s32, v191
	v_add_f32_e32 v181, s32, v192
	v_add_f32_e32 v186, s32, v193
	v_add_f32_e32 v140, s32, v140
	v_add_f32_e32 v141, s32, v141
	v_add_f32_e32 v187, s32, v142
	v_add_f32_e32 v188, s32, v143
	v_add_f32_e32 v217, s32, v136
	v_add_f32_e32 v218, s32, v137
	v_add_f32_e32 v138, s32, v138
	v_add_f32_e32 v219, s32, v139
	v_add_f32_e32 v220, s32, v132
	v_add_f32_e32 v221, s32, v133
	v_add_f32_e32 v222, s32, v134
	v_add_f32_e32 v223, s32, v135
	v_max3_f32 v29, v30, s82, v180
	v_max3_f32 v29, v29, v181, v186
	v_max3_f32 v29, v29, v140, v141
	v_max3_f32 v29, v29, v187, v188
	v_max3_f32 v29, v29, v217, v218
	v_max3_f32 v29, v29, v138, v219
	v_max3_f32 v29, v29, v220, v221
	v_max3_f32 v29, v29, v222, v223
	s_branch .Lb3e_2
.Lb3s_2:
	v_sub_u32_e32 v239, v160, v189
	v_med3_i32 v239, v239, 0, v207
	v_lshl_add_u32 v239, v239, 2, v151
	ds_read_b32 v182, v239 offset:9216
	v_or_b32_e32 v240, 1, v189
	v_sub_u32_e32 v240, v160, v240
	v_med3_i32 v240, v240, 0, v207
	v_lshl_add_u32 v240, v240, 2, v151
	ds_read_b32 v240, v240 offset:9216
	v_or_b32_e32 v241, 2, v189
	v_sub_u32_e32 v241, v160, v241
	v_med3_i32 v241, v241, 0, v207
	v_lshl_add_u32 v241, v241, 2, v151
	ds_read_b32 v241, v241 offset:9216
	v_or_b32_e32 v242, 3, v189
	v_sub_u32_e32 v242, v160, v242
	v_med3_i32 v242, v242, 0, v207
	v_lshl_add_u32 v242, v242, 2, v151
	ds_read_b32 v242, v242 offset:9216
	v_sub_u32_e32 v243, v175, v189
	v_med3_i32 v243, v243, 0, v207
	v_lshl_add_u32 v243, v243, 2, v151
	ds_read_b32 v243, v243 offset:9216
	v_add_u32_e32 v247, 17, v189
	v_sub_u32_e32 v247, v160, v247
	v_med3_i32 v247, v247, 0, v207
	v_lshl_add_u32 v247, v247, 2, v151
	ds_read_b32 v247, v247 offset:9216
	v_add_u32_e32 v248, 18, v189
	v_sub_u32_e32 v248, v160, v248
	v_med3_i32 v248, v248, 0, v207
	v_lshl_add_u32 v248, v248, 2, v151
	ds_read_b32 v248, v248 offset:9216
	v_add_u32_e32 v249, 19, v189
	v_sub_u32_e32 v249, v160, v249
	v_med3_i32 v249, v249, 0, v207
	v_lshl_add_u32 v249, v249, 2, v151
	ds_read_b32 v249, v249 offset:9216
	v_add_u32_e32 v250, 32, v189
	v_sub_u32_e32 v250, v160, v250
	v_med3_i32 v250, v250, 0, v207
	v_lshl_add_u32 v250, v250, 2, v151
	ds_read_b32 v250, v250 offset:9216
	v_add_u32_e32 v251, 33, v189
	v_sub_u32_e32 v251, v160, v251
	v_med3_i32 v251, v251, 0, v207
	v_lshl_add_u32 v251, v251, 2, v151
	ds_read_b32 v251, v251 offset:9216
	v_add_u32_e32 v252, 34, v189
	v_sub_u32_e32 v252, v160, v252
	v_med3_i32 v252, v252, 0, v207
	v_lshl_add_u32 v252, v252, 2, v151
	ds_read_b32 v252, v252 offset:9216
	v_add_u32_e32 v253, 35, v189
	v_sub_u32_e32 v253, v160, v253
	v_med3_i32 v253, v253, 0, v207
	v_lshl_add_u32 v253, v253, 2, v151
	ds_read_b32 v253, v253 offset:9216
	v_add_u32_e32 v254, 48, v189
	v_sub_u32_e32 v254, v160, v254
	v_med3_i32 v254, v254, 0, v207
	v_lshl_add_u32 v254, v254, 2, v151
	ds_read_b32 v254, v254 offset:9216
	v_add_u32_e32 v255, 49, v189
	v_sub_u32_e32 v255, v160, v255
	v_med3_i32 v255, v255, 0, v207
	v_lshl_add_u32 v255, v255, 2, v151
	ds_read_b32 v255, v255 offset:9216
	v_sub_u32_e32 v29, v160, v189
	v_cmp_gt_u32_e64 s[8:9], s75, v29
	v_sub_u32_e32 v187, v175, v189
	v_add_u32_e32 v213, 17, v189
	v_add_u32_e32 v214, 18, v189
	v_add_u32_e32 v215, 19, v189
	s_waitcnt lgkmcnt(13)
	v_add_f32_e32 v29, v190, v182
	v_or_b32_e32 v190, 1, v189
	v_cndmask_b32_e64 v30, v208, v29, s[8:9]
	v_sub_u32_e32 v29, v160, v190
	v_cmp_gt_u32_e32 vcc, s75, v29
	v_add_u32_e32 v216, 32, v189
	v_add_u32_e32 v194, 34, v189
	v_add_u32_e32 v195, 35, v189
	v_add_u32_e32 v209, 48, v189
	s_waitcnt lgkmcnt(12)
	v_add_f32_e32 v29, v191, v240
	v_or_b32_e32 v191, 2, v189
	v_sub_u32_e32 v181, v160, v191
	v_cndmask_b32_e32 v180, v208, v29, vcc
	v_cmp_gt_u32_e32 vcc, s75, v181
	v_add_u32_e32 v210, 49, v189
	v_add_u32_e32 v211, 50, v189
	v_add_u32_e32 v212, 51, v189
	v_max3_f32 v29, v30, s82, v180
	s_waitcnt lgkmcnt(11)
	v_add_f32_e32 v181, v192, v241
	v_or_b32_e32 v192, 3, v189
	v_sub_u32_e32 v186, v160, v192
	v_cndmask_b32_e32 v181, v208, v181, vcc
	v_cmp_gt_u32_e32 vcc, s75, v186
	s_waitcnt lgkmcnt(10)
	v_add_f32_e32 v186, v193, v242
	v_cndmask_b32_e32 v186, v208, v186, vcc
	v_cmp_gt_u32_e32 vcc, s75, v187
	v_add_u32_e32 v193, 33, v189
	v_max3_f32 v29, v29, v181, v186
	s_waitcnt lgkmcnt(9)
	v_add_f32_e32 v140, v140, v243
	v_sub_u32_e32 v187, v160, v213
	v_cndmask_b32_e32 v140, v208, v140, vcc
	v_cmp_gt_u32_e32 vcc, s75, v187
	s_waitcnt lgkmcnt(8)
	v_add_f32_e32 v141, v141, v247
	v_sub_u32_e32 v187, v160, v214
	v_cndmask_b32_e32 v141, v208, v141, vcc
	v_cmp_gt_u32_e32 vcc, s75, v187
	v_max3_f32 v29, v29, v140, v141
	s_waitcnt lgkmcnt(7)
	v_add_f32_e32 v142, v142, v248
	v_cndmask_b32_e32 v187, v208, v142, vcc
	v_sub_u32_e32 v142, v160, v215
	v_cmp_gt_u32_e32 vcc, s75, v142
	s_waitcnt lgkmcnt(6)
	v_add_f32_e32 v142, v143, v249
	v_cndmask_b32_e32 v188, v208, v142, vcc
	v_sub_u32_e32 v142, v160, v216
	v_cmp_gt_u32_e32 vcc, s75, v142
	v_max3_f32 v29, v29, v187, v188
	s_waitcnt lgkmcnt(5)
	v_add_f32_e32 v136, v136, v250
	v_cndmask_b32_e32 v217, v208, v136, vcc
	v_sub_u32_e32 v136, v160, v193
	v_cmp_gt_u32_e32 vcc, s75, v136
	s_waitcnt lgkmcnt(4)
	v_add_f32_e32 v136, v137, v251
	v_cndmask_b32_e32 v218, v208, v136, vcc
	v_sub_u32_e32 v136, v160, v194
	v_cmp_gt_u32_e32 vcc, s75, v136
	v_max3_f32 v29, v29, v217, v218
	s_waitcnt lgkmcnt(3)
	v_add_f32_e32 v136, v138, v252
	v_cndmask_b32_e32 v138, v208, v136, vcc
	v_sub_u32_e32 v136, v160, v195
	v_cmp_gt_u32_e32 vcc, s75, v136
	s_waitcnt lgkmcnt(2)
	v_add_f32_e32 v136, v139, v253
	v_cndmask_b32_e32 v219, v208, v136, vcc
	v_sub_u32_e32 v136, v160, v209
	v_cmp_gt_u32_e32 vcc, s75, v136
	v_max3_f32 v29, v29, v138, v219
	s_waitcnt lgkmcnt(1)
	v_add_f32_e32 v132, v132, v254
	v_cndmask_b32_e32 v220, v208, v132, vcc
	v_sub_u32_e32 v132, v160, v210
	v_cmp_gt_u32_e32 vcc, s75, v132
	s_waitcnt lgkmcnt(0)
	v_add_f32_e32 v132, v133, v255
	v_cndmask_b32_e32 v221, v208, v132, vcc
	v_sub_u32_e32 v132, v160, v211
	v_cmp_gt_u32_e32 vcc, s75, v132
	v_med3_i32 v132, v132, 0, v207
	v_lshl_add_u32 v132, v132, 2, v151
	ds_read_b32 v132, v132 offset:9216
	v_max3_f32 v29, v29, v220, v221
	s_waitcnt lgkmcnt(0)
	v_add_f32_e32 v132, v134, v132
	v_cndmask_b32_e32 v222, v208, v132, vcc
	v_sub_u32_e32 v132, v160, v212
	v_cmp_gt_u32_e32 vcc, s75, v132
	v_med3_i32 v132, v132, 0, v207
	v_lshl_add_u32 v132, v132, 2, v151
	ds_read_b32 v132, v132 offset:9216
	s_waitcnt lgkmcnt(0)
	v_add_f32_e32 v132, v135, v132
	v_cndmask_b32_e32 v223, v208, v132, vcc
	v_max3_f32 v29, v29, v222, v223
.Lb3e_2:
	v_mov_b32_e32 v132, v29
	s_nop 1
	v_permlane16_swap_b32_e32 v29, v132
	v_max_f32_e32 v132, v132, v132
	v_max_f32_e32 v29, v29, v29
	v_max_f32_e32 v29, v29, v132
	v_mov_b32_e32 v132, v29
	s_nop 1
	v_permlane32_swap_b32_e32 v29, v132
	v_max3_f32 v29, v183, v29, v132
	v_cmp_lt_f32_e32 vcc, s51, v30
	v_sub_f32_e32 v30, v30, v29
	v_mul_f32_e32 v30, 0x3fb8aa3b, v30
	v_sub_f32_e32 v133, v180, v29
	v_exp_f32_e32 v30, v30
	v_mul_f32_e32 v133, 0x3fb8aa3b, v133
	v_sub_f32_e32 v134, v181, v29
	v_exp_f32_e32 v133, v133
	v_mul_f32_e32 v134, 0x3fb8aa3b, v134
	v_sub_f32_e32 v135, v186, v29
	v_exp_f32_e32 v134, v134
	v_mul_f32_e32 v135, 0x3fb8aa3b, v135
	v_sub_f32_e32 v132, v183, v29
	v_exp_f32_e32 v135, v135
	v_mul_f32_e32 v224, 0x3fb8aa3b, v132
	v_cndmask_b32_e32 v132, 0, v30, vcc
	v_cmp_lt_f32_e32 vcc, s51, v180
	v_sub_f32_e32 v139, v218, v29
	v_mul_f32_e32 v139, 0x3fb8aa3b, v139
	v_cndmask_b32_e32 v133, 0, v133, vcc
	v_cmp_lt_f32_e32 vcc, s51, v181
	v_exp_f32_e32 v139, v139
	v_add_f32_e32 v30, 0, v132
	v_cndmask_b32_e32 v134, 0, v134, vcc
	v_cmp_lt_f32_e32 vcc, s51, v186
	v_add_f32_e32 v30, v133, v30
	v_add_f32_e32 v30, v134, v30
	v_cndmask_b32_e32 v136, 0, v135, vcc
	v_sub_f32_e32 v135, v140, v29
	v_mul_f32_e32 v135, 0x3fb8aa3b, v135
	v_exp_f32_e32 v135, v135
	v_cmp_lt_f32_e32 vcc, s51, v140
	v_add_f32_e32 v30, v136, v30
	s_nop 0
	v_cndmask_b32_e32 v137, 0, v135, vcc
	v_sub_f32_e32 v135, v141, v29
	v_mul_f32_e32 v135, 0x3fb8aa3b, v135
	v_exp_f32_e32 v135, v135
	v_cmp_lt_f32_e32 vcc, s51, v141
	v_add_f32_e32 v30, v137, v30
	s_nop 0
	v_cndmask_b32_e32 v142, 0, v135, vcc
	v_sub_f32_e32 v135, v187, v29
	v_mul_f32_e32 v135, 0x3fb8aa3b, v135
	v_exp_f32_e32 v135, v135
	v_cmp_lt_f32_e32 vcc, s51, v187
	v_add_f32_e32 v30, v142, v30
	s_nop 0
	v_cndmask_b32_e32 v143, 0, v135, vcc
	v_sub_f32_e32 v135, v188, v29
	v_mul_f32_e32 v135, 0x3fb8aa3b, v135
	v_exp_f32_e32 v135, v135
	v_cmp_lt_f32_e32 vcc, s51, v188
	v_add_f32_e32 v30, v143, v30
	s_nop 0
	v_cndmask_b32_e32 v183, 0, v135, vcc
	v_sub_f32_e32 v135, v217, v29
	v_mul_f32_e32 v135, 0x3fb8aa3b, v135
	v_exp_f32_e32 v135, v135
	v_cmp_lt_f32_e32 vcc, s51, v217
	v_add_f32_e32 v30, v183, v30
	s_nop 0
	v_cndmask_b32_e32 v135, 0, v135, vcc
	v_cmp_lt_f32_e32 vcc, s51, v218
	v_add_f32_e32 v30, v135, v30
	s_nop 0
	v_cndmask_b32_e32 v139, 0, v139, vcc
	v_cmp_lt_f32_e32 vcc, s51, v138
	v_sub_f32_e32 v138, v138, v29
	v_mul_f32_e32 v138, 0x3fb8aa3b, v138
	v_exp_f32_e32 v138, v138
	v_add_f32_e32 v30, v139, v30
	v_cndmask_b32_e32 v141, 0, v138, vcc
	v_sub_f32_e32 v138, v219, v29
	v_mul_f32_e32 v138, 0x3fb8aa3b, v138
	v_exp_f32_e32 v138, v138
	v_cmp_lt_f32_e32 vcc, s51, v219
	v_add_f32_e32 v30, v141, v30
	s_nop 0
	v_cndmask_b32_e32 v180, 0, v138, vcc
	v_sub_f32_e32 v138, v220, v29
	v_mul_f32_e32 v138, 0x3fb8aa3b, v138
	v_exp_f32_e32 v138, v138
	v_cmp_lt_f32_e32 vcc, s51, v220
	v_add_f32_e32 v30, v180, v30
	s_nop 0
	v_cndmask_b32_e32 v181, 0, v138, vcc
	v_sub_f32_e32 v138, v221, v29
	v_mul_f32_e32 v138, 0x3fb8aa3b, v138
	v_exp_f32_e32 v138, v138
	v_cmp_lt_f32_e32 vcc, s51, v221
	v_add_f32_e32 v30, v181, v30
	s_nop 0
	v_cndmask_b32_e32 v186, 0, v138, vcc
	v_sub_f32_e32 v138, v222, v29
	v_mul_f32_e32 v138, 0x3fb8aa3b, v138
	v_exp_f32_e32 v138, v138
	v_cmp_lt_f32_e32 vcc, s51, v222
	v_add_f32_e32 v30, v186, v30
	s_nop 0
	v_cndmask_b32_e32 v187, 0, v138, vcc
	v_sub_f32_e32 v138, v223, v29
	v_mul_f32_e32 v138, 0x3fb8aa3b, v138
	v_exp_f32_e32 v138, v138
	v_cmp_lt_f32_e32 vcc, s51, v223
	v_add_f32_e32 v30, v187, v30
	s_nop 0
	v_cndmask_b32_e32 v188, 0, v138, vcc
	v_add_f32_e32 v138, v188, v30
	v_exp_f32_e32 v30, v224
	v_mov_b32_e32 v140, v138
	s_nop 1
	v_permlane16_swap_b32_e32 v138, v140
	v_add_f32_e32 v138, v138, v140
	v_mov_b32_e32 v140, v138
	s_nop 1
	v_permlane32_swap_b32_e32 v138, v140
	v_cmp_neq_f32_e32 vcc, 1.0, v30
	s_cbranch_vccz .LBB0_706
	v_pk_mul_f32 v[98:99], v[98:99], v[30:31] op_sel_hi:[1,0]
	v_pk_mul_f32 v[96:97], v[96:97], v[30:31] op_sel_hi:[1,0]
	v_pk_mul_f32 v[94:95], v[94:95], v[30:31] op_sel_hi:[1,0]
	v_pk_mul_f32 v[92:93], v[92:93], v[30:31] op_sel_hi:[1,0]
	v_pk_mul_f32 v[90:91], v[90:91], v[30:31] op_sel_hi:[1,0]
	v_pk_mul_f32 v[88:89], v[88:89], v[30:31] op_sel_hi:[1,0]
	v_pk_mul_f32 v[86:87], v[86:87], v[30:31] op_sel_hi:[1,0]
	v_pk_mul_f32 v[84:85], v[84:85], v[30:31] op_sel_hi:[1,0]
	v_pk_mul_f32 v[82:83], v[82:83], v[30:31] op_sel_hi:[1,0]
	v_pk_mul_f32 v[80:81], v[80:81], v[30:31] op_sel_hi:[1,0]
	v_pk_mul_f32 v[78:79], v[78:79], v[30:31] op_sel_hi:[1,0]
	v_pk_mul_f32 v[76:77], v[76:77], v[30:31] op_sel_hi:[1,0]
	v_pk_mul_f32 v[74:75], v[74:75], v[30:31] op_sel_hi:[1,0]
	v_pk_mul_f32 v[72:73], v[72:73], v[30:31] op_sel_hi:[1,0]
	v_pk_mul_f32 v[70:71], v[70:71], v[30:31] op_sel_hi:[1,0]
	v_pk_mul_f32 v[68:69], v[68:69], v[30:31] op_sel_hi:[1,0]
.LBB0_706:
	s_lshl_b32 s98, s2, 6
	s_sub_i32 s98, s99, s98
	s_add_i32 s98, s98, 0xffffff41
	s_cmp_lt_u32 s98, 0x122
	s_cbranch_scc0 .Lb3s_3
	v_add_f32_e32 v124, s32, v124
	v_add_f32_e32 v128, s32, v128
	v_add_f32_e32 v129, s32, v129
	v_add_f32_e32 v130, s32, v130
	v_add_f32_e32 v131, s32, v131
	v_add_f32_e32 v125, s32, v125
	v_add_f32_e32 v126, s32, v126
	v_add_f32_e32 v127, s32, v127
	v_add_f32_e32 v189, s32, v120
	v_add_f32_e32 v190, s32, v121
	v_add_f32_e32 v191, s32, v122
	v_add_f32_e32 v192, s32, v123
	v_add_f32_e32 v116, s32, v116
	v_add_f32_e32 v193, s32, v117
	v_add_f32_e32 v194, s32, v118
	v_add_f32_e32 v195, s32, v119
	v_max3_f32 v117, v124, s82, v128
	v_max3_f32 v117, v117, v129, v130
	v_max3_f32 v117, v117, v131, v125
	v_max3_f32 v117, v117, v126, v127
	v_max3_f32 v117, v117, v189, v190
	v_max3_f32 v117, v117, v191, v192
	v_max3_f32 v117, v117, v116, v193
	v_max3_f32 v117, v117, v194, v195
	s_branch .Lb3e_3

.Lb3e_3:
	v_mov_b32_e32 v118, v117
	s_nop 1
	v_permlane16_swap_b32_e32 v117, v118
	v_max_f32_e32 v118, v118, v118
	v_max_f32_e32 v117, v117, v117
	v_max_f32_e32 v117, v117, v118
	v_mov_b32_e32 v118, v117
	s_nop 1
	v_permlane32_swap_b32_e32 v117, v118
	v_max3_f32 v182, v31, v117, v118
	v_sub_f32_e32 v31, v31, v182
	v_mul_f32_e32 v209, 0x3fb8aa3b, v31
	v_sub_f32_e32 v31, v128, v182
	v_mul_f32_e32 v31, 0x3fb8aa3b, v31
	v_sub_f32_e32 v117, v129, v182
	v_exp_f32_e32 v31, v31
	v_mul_f32_e32 v117, 0x3fb8aa3b, v117
	v_exp_f32_e32 v117, v117
	v_cmp_lt_f32_e32 vcc, s51, v128
	v_sub_f32_e32 v120, v131, v182
	v_mul_f32_e32 v120, 0x3fb8aa3b, v120
	v_cndmask_b32_e32 v31, 0, v31, vcc
	v_cmp_lt_f32_e32 vcc, s51, v129
	v_add_f32_e32 v118, 0, v31
	v_sub_f32_e32 v121, v124, v182
	v_cndmask_b32_e32 v117, 0, v117, vcc
	v_add_f32_e32 v119, v117, v118
	v_sub_f32_e32 v118, v130, v182
	v_mul_f32_e32 v118, 0x3fb8aa3b, v118
	v_exp_f32_e32 v118, v118
	v_exp_f32_e32 v120, v120
	v_mul_f32_e32 v121, 0x3fb8aa3b, v121
	v_sub_f32_e32 v122, v125, v182
	v_exp_f32_e32 v121, v121
	v_mul_f32_e32 v122, 0x3fb8aa3b, v122
	v_cmp_lt_f32_e32 vcc, s51, v130
	v_exp_f32_e32 v122, v122
	s_nop 0
	v_cndmask_b32_e32 v118, 0, v118, vcc
	v_cmp_lt_f32_e32 vcc, s51, v131
	v_add_f32_e32 v119, v118, v119
	s_nop 0
	v_cndmask_b32_e32 v120, 0, v120, vcc
	v_cmp_lt_f32_e32 vcc, s51, v124
	v_add_f32_e32 v119, v120, v119
	s_nop 0
	v_cndmask_b32_e32 v121, 0, v121, vcc
	v_cmp_lt_f32_e32 vcc, s51, v125
	v_add_f32_e32 v119, v121, v119
	v_sub_f32_e32 v125, v192, v182
	v_cndmask_b32_e32 v128, 0, v122, vcc
	v_sub_f32_e32 v122, v126, v182
	v_mul_f32_e32 v122, 0x3fb8aa3b, v122
	v_exp_f32_e32 v122, v122
	v_cmp_lt_f32_e32 vcc, s51, v126
	v_add_f32_e32 v119, v128, v119
	v_mul_f32_e32 v125, 0x3fb8aa3b, v125
	v_cndmask_b32_e32 v126, 0, v122, vcc
	v_sub_f32_e32 v122, v127, v182
	v_mul_f32_e32 v122, 0x3fb8aa3b, v122
	v_exp_f32_e32 v122, v122
	v_cmp_lt_f32_e32 vcc, s51, v127
	v_add_f32_e32 v119, v126, v119
	v_exp_f32_e32 v125, v125
	v_cndmask_b32_e32 v130, 0, v122, vcc
	v_add_f32_e32 v122, v130, v119
	v_sub_f32_e32 v119, v189, v182
	v_mul_f32_e32 v119, 0x3fb8aa3b, v119
	v_exp_f32_e32 v119, v119
	v_cmp_lt_f32_e32 vcc, s51, v189
	s_nop 1
	v_cndmask_b32_e32 v119, 0, v119, vcc
	v_add_f32_e32 v123, v119, v122
	v_sub_f32_e32 v122, v190, v182
	v_mul_f32_e32 v122, 0x3fb8aa3b, v122
	v_exp_f32_e32 v122, v122
	v_cmp_lt_f32_e32 vcc, s51, v190
	s_nop 1
	v_cndmask_b32_e32 v122, 0, v122, vcc
	v_add_f32_e32 v124, v122, v123
	v_sub_f32_e32 v123, v191, v182
	v_mul_f32_e32 v123, 0x3fb8aa3b, v123
	v_exp_f32_e32 v123, v123
	v_cmp_lt_f32_e32 vcc, s51, v191
	s_nop 1
	v_cndmask_b32_e32 v123, 0, v123, vcc
	v_cmp_lt_f32_e32 vcc, s51, v192
	v_add_f32_e32 v124, v123, v124
	s_nop 0
	v_cndmask_b32_e32 v127, 0, v125, vcc
	v_cmp_lt_f32_e32 vcc, s51, v116
	v_sub_f32_e32 v116, v116, v182
	v_mul_f32_e32 v116, 0x3fb8aa3b, v116
	v_exp_f32_e32 v116, v116
	v_add_f32_e32 v124, v127, v124
	v_cndmask_b32_e32 v129, 0, v116, vcc
	v_add_f32_e32 v116, v129, v124
	v_sub_f32_e32 v124, v193, v182
	v_mul_f32_e32 v124, 0x3fb8aa3b, v124
	v_exp_f32_e32 v124, v124
	v_cmp_lt_f32_e32 vcc, s51, v193
	s_nop 1
	v_cndmask_b32_e32 v131, 0, v124, vcc
	v_sub_f32_e32 v124, v194, v182
	v_mul_f32_e32 v124, 0x3fb8aa3b, v124
	v_exp_f32_e32 v124, v124
	v_cmp_lt_f32_e32 vcc, s51, v194
	v_add_f32_e32 v116, v131, v116
	s_nop 0
	v_cndmask_b32_e32 v189, 0, v124, vcc
	v_sub_f32_e32 v124, v195, v182
	v_mul_f32_e32 v124, 0x3fb8aa3b, v124
	v_exp_f32_e32 v124, v124
	v_cmp_lt_f32_e32 vcc, s51, v195
	v_add_f32_e32 v116, v189, v116
	s_nop 0
	v_cndmask_b32_e32 v190, 0, v124, vcc
	v_add_f32_e32 v124, v190, v116
	v_exp_f32_e32 v116, v209
	v_mov_b32_e32 v125, v124
	s_nop 1
	v_permlane16_swap_b32_e32 v124, v125
	v_add_f32_e32 v124, v124, v125
	v_mov_b32_e32 v125, v124
	s_nop 1
	v_permlane32_swap_b32_e32 v124, v125
	v_cmp_neq_f32_e32 vcc, 1.0, v116
	s_cbranch_vccz .LBB0_708
	v_pk_mul_f32 v[66:67], v[66:67], v[116:117] op_sel_hi:[1,0]
	v_pk_mul_f32 v[64:65], v[64:65], v[116:117] op_sel_hi:[1,0]
	v_pk_mul_f32 v[62:63], v[62:63], v[116:117] op_sel_hi:[1,0]
	v_pk_mul_f32 v[60:61], v[60:61], v[116:117] op_sel_hi:[1,0]
	v_pk_mul_f32 v[58:59], v[58:59], v[116:117] op_sel_hi:[1,0]
	v_pk_mul_f32 v[56:57], v[56:57], v[116:117] op_sel_hi:[1,0]
	v_pk_mul_f32 v[54:55], v[54:55], v[116:117] op_sel_hi:[1,0]
	v_pk_mul_f32 v[52:53], v[52:53], v[116:117] op_sel_hi:[1,0]
	v_pk_mul_f32 v[50:51], v[50:51], v[116:117] op_sel_hi:[1,0]
	v_pk_mul_f32 v[48:49], v[48:49], v[116:117] op_sel_hi:[1,0]
	v_pk_mul_f32 v[46:47], v[46:47], v[116:117] op_sel_hi:[1,0]
	v_pk_mul_f32 v[44:45], v[44:45], v[116:117] op_sel_hi:[1,0]
	v_pk_mul_f32 v[42:43], v[42:43], v[116:117] op_sel_hi:[1,0]
	v_pk_mul_f32 v[40:41], v[40:41], v[116:117] op_sel_hi:[1,0]
	v_pk_mul_f32 v[38:39], v[38:39], v[116:117] op_sel_hi:[1,0]
	v_pk_mul_f32 v[36:37], v[36:37], v[116:117] op_sel_hi:[1,0]
